# barrier arrival: first poll of the arrival counter issued together with the arrival atomic (saves one round trip for late arrivers)
# baseline (speedup 1.0000x reference)
; DEVI unsigned xb_ld(unsigned* p) { return __hip_atomic_load(p, __ATOMIC_RELAXED, __HIP_MEMORY_SCOPE_AGENT); }
; DEVI unsigned xb_add(unsigned* p, unsigned v) { return __hip_atomic_fetch_add(p, v, __ATOMIC_RELAXED, __HIP_MEMORY_SCOPE_AGENT); }
; #define XB_SPIN(cond, bar) do { unsigned _sp = 0; while (cond) { __builtin_amdgcn_s_sleep(1); \
;     if ((++_sp & 255u) == 0u) { if (xb_ld(&(bar)[XB_TMO])) break; if (_sp > XB_SPIN_CAP) { atomicAdd(&(bar)[XB_TMO], 1u); break; } } } } while (0)
; DEVI void xcd_barrier(const XcdBarrier& b) {
;     ...
;     const unsigned old = xb_add(&bar[XB_XSUB(b.x)], 1u);
;     const unsigned gen = old / nloc;
;     if (old + 1u == (gen + 1u) * nloc) {
;       __builtin_amdgcn_fence(__ATOMIC_RELEASE, "agent");
;       asm volatile("s_waitcnt vmcnt(0)" ::: "memory");
;       const unsigned og = xb_add(&bar[XB_TOP], 1u);
;       const unsigned tg = og / nx;
;       if (og + 1u == (tg + 1u) * nx) xb_add(&bar[XB_TOPGEN], 1u);
;       else XB_SPIN(xb_ld(&bar[XB_TOPGEN]) == tg, bar);
;       __builtin_amdgcn_fence(__ATOMIC_ACQUIRE, "agent");
;       xb_add(&bar[XB_XGEN(b.x)], 1u);
;       asm volatile("s_waitcnt vmcnt(0)" ::: "memory");
;     } else {
;       XB_SPIN(xb_ld(&bar[XB_XGEN(b.x)]) == gen, bar);
.LBB0_945:
	s_mov_b64 s[38:39], exec
	v_mbcnt_lo_u32_b32 v0, s38, 0
	v_mbcnt_hi_u32_b32 v0, s39, v0
	v_cmp_eq_u32_e32 vcc, 0, v0
	s_and_saveexec_b64 s[36:37], vcc
	s_cbranch_execz .LBB0_947
	s_bcnt1_i32_b64 s20, s[38:39]
	v_mov_b32_e32 v4, s20
	v_readlane_b32 s20, v242, 22
	v_readlane_b32 s21, v242, 23
	s_nop 4
	global_atomic_add v4, v1, v4, s[20:21] sc0
	global_load_dword v7, v1, s[20:21] sc1
	buffer_inv sc1
.LBB0_947:
	s_or_b64 exec, exec, s[36:37]
	v_cvt_f32_u32_e32 v5, v3
	s_waitcnt vmcnt(0)
	v_readfirstlane_b32 s20, v4
	v_sub_u32_e32 v4, 0, v3
	v_rcp_iflag_f32_e32 v5, v5
	v_add_u32_e32 v6, s20, v0
	v_mul_f32_e32 v5, 0x4f7ffffe, v5
	v_cvt_u32_f32_e32 v5, v5
	v_mul_lo_u32 v0, v4, v5
	v_mul_hi_u32 v0, v5, v0
	v_add_u32_e32 v0, v5, v0
	v_mul_hi_u32 v0, v6, v0
	v_mul_lo_u32 v4, v0, v3
	v_sub_u32_e32 v4, v6, v4
	v_add_u32_e32 v5, 1, v0
	v_cmp_ge_u32_e32 vcc, v4, v3
	s_nop 1
	v_cndmask_b32_e32 v0, v0, v5, vcc
	v_sub_u32_e32 v5, v4, v3
	v_cndmask_b32_e32 v4, v4, v5, vcc
	v_add_u32_e32 v5, 1, v0
	v_cmp_ge_u32_e32 vcc, v4, v3
	v_add_u32_e32 v4, 1, v6
	s_nop 0
	v_cndmask_b32_e32 v0, v0, v5, vcc
	v_mul_lo_u32 v5, v3, v0
	v_add_u32_e32 v3, v5, v3
	v_cmp_ne_u32_e32 vcc, v4, v3
	s_and_saveexec_b64 s[26:27], vcc
	s_xor_b64 s[36:37], exec, s[26:27]
	s_cbranch_execz .LBB0_961
	s_and_b32 s20, s92, 7
	s_cmp_eq_u32 s20, 0
	s_cbranch_scc1 .Lxs_nolocal
	s_cmp_eq_u32 s20, 1
	s_cbranch_scc1 .Lxs_nolocal
	s_cmp_eq_u32 s20, 6
	s_cbranch_scc1 .Lxs_nolocal
	v_readfirstlane_b32 s20, v246
	s_bcnt1_i32_b32 s20, s20
	s_cmp_lg_u32 s20, 1
	s_cbranch_scc1 .Lxs_nolocal
	v_readfirstlane_b32 s20, v247
	s_bcnt1_i32_b32 s20, s20
	s_cmp_lg_u32 s20, 1
	s_cbranch_scc1 .Lxs_nolocal
	v_readfirstlane_b32 s20, v248
	s_bcnt1_i32_b32 s20, s20
	s_cmp_lg_u32 s20, 1
	s_cbranch_scc1 .Lxs_nolocal
	v_readfirstlane_b32 s20, v249
	s_bcnt1_i32_b32 s20, s20
	s_cmp_lg_u32 s20, 1
	s_cbranch_scc1 .Lxs_nolocal
	v_readfirstlane_b32 s20, v250
	s_bcnt1_i32_b32 s20, s20
	s_cmp_lg_u32 s20, 1
	s_cbranch_scc1 .Lxs_nolocal
	v_readfirstlane_b32 s20, v251
	s_bcnt1_i32_b32 s20, s20
	s_cmp_lg_u32 s20, 1
	s_cbranch_scc1 .Lxs_nolocal
	v_readfirstlane_b32 s20, v252
	s_bcnt1_i32_b32 s20, s20
	s_cmp_lg_u32 s20, 1
	s_cbranch_scc1 .Lxs_nolocal
	v_readfirstlane_b32 s20, v253
	s_bcnt1_i32_b32 s20, s20
	s_cmp_lg_u32 s20, 1
	s_cbranch_scc1 .Lxs_nolocal
	v_readlane_b32 s20, v242, 22
	v_readlane_b32 s21, v242, 23
	s_mov_b64 s[38:39], exec
	s_waitcnt lgkmcnt(0)
	v_cmp_lt_u32_e32 vcc, v7, v3
	s_cbranch_vccz .LBB0_960
	s_nop 4
